# v33 + WGs without a ctx split-K sub-unit (c>=128) sleep ~30us at the start of the 4 ctx-split phases so main units run in step with the ctx WGs (shared L2 panels)
# baseline (speedup 1.0000x reference)
;     __device__ __forceinline__ void operator()(const f32x4 (&acc)[2][2][4][2], const Unit& u, int wr, int wc, int fr, int fq) const {
;         float* xo = part + (size_t)u.q * MC * DM + (size_t)u.pm * BM * DM;
;         const int r0 = wr * 64 + fr, col0 = u.pn * BM + wc * 32 + 4 * fq;
;         const float* gp = gate + col0;
; #pragma unroll
;         for (int bj = 0; bj < 2; ++bj)
; #pragma unroll
;             for (int n = 0; n < 2; ++n) { const f32x4 gv = *(const f32x4*)(gp + bj * HALF + n * 16) * gs;
; #pragma unroll
;                 for (int ai = 0; ai < 2; ++ai)
; #pragma unroll
;                     for (int m = 0; m < 4; ++m) *(f32x4*)(xo + (size_t)(r0 + ai * HALF + m * 16) * DM + col0 + bj * HALF + n * 16) = gv * acc[ai][bj][m][n]; }
;     }
.LBB0_291:
	s_lshl_b32 s2, s1, 23
	s_and_b32 s2, s2, 0x1800000
	s_add_u32 s2, s73, s2
	v_readlane_b32 s3, v252, 14
	s_addc_u32 s3, s3, 0
	s_lshl_b32 s4, s12, 21
	s_add_u32 s2, s2, s4
	v_or_b32_e32 v130, 16, v134
	s_addc_u32 s3, s3, 0
	s_lshl_b32 s0, s0, 8
	v_ashrrev_i32_e32 v131, 31, v130
	v_lshl_or_b32 v1, v1, 2, s0
	v_or_b32_e32 v132, 32, v134
	v_lshlrev_b64 v[140:141], 13, v[130:131]
	v_or_b32_e32 v130, s15, v1
	v_ashrrev_i32_e32 v133, 31, v132
	v_ashrrev_i32_e32 v131, 31, v130
	v_ashrrev_i32_e32 v135, 31, v134
	v_lshlrev_b64 v[142:143], 13, v[132:133]
	v_lshlrev_b64 v[132:133], 2, v[130:131]
	v_or_b32_e32 v136, 48, v134
	v_lshlrev_b64 v[138:139], 13, v[134:135]
	v_lshl_add_u64 v[134:135], s[48:49], 0, v[132:133]
	s_mov_b32 s0, 0x8c000
	v_lshl_add_u64 v[144:145], s[2:3], 0, v[132:133]
	v_add_co_u32_e32 v132, vcc, s0, v134
	s_mov_b64 s[4:5], 0x8c000
	s_nop 0
	v_addc_co_u32_e32 v133, vcc, 0, v135, vcc
	v_lshl_add_u64 v[130:131], v[134:135], 0, s[4:5]
	global_load_dwordx4 v[132:135], v[132:133], off
	v_ashrrev_i32_e32 v137, 31, v136
	v_lshlrev_b64 v[136:137], 13, v[136:137]
	s_mov_b32 s0, 0x100000
	s_mov_b64 s[2:3], 0x100000
	s_waitcnt vmcnt(0)
	v_pk_mul_f32 v[146:147], v[134:135], 0.5 op_sel_hi:[1,0]
	v_pk_mul_f32 v[148:149], v[132:133], 0.5 op_sel_hi:[1,0]
	v_pk_mul_f32 v[134:135], v[128:129], v[146:147]
	v_pk_mul_f32 v[132:133], v[126:127], v[148:149]
	v_lshl_add_u64 v[126:127], v[144:145], 0, v[138:139]
	global_store_dwordx4 v[126:127], v[132:135], off
	s_nop 1
	v_pk_mul_f32 v[134:135], v[124:125], v[146:147]
	v_pk_mul_f32 v[132:133], v[122:123], v[148:149]
	v_lshl_add_u64 v[122:123], v[144:145], 0, v[140:141]
	global_store_dwordx4 v[122:123], v[132:135], off
	s_nop 1
	v_pk_mul_f32 v[134:135], v[120:121], v[146:147]
	v_pk_mul_f32 v[132:133], v[118:119], v[148:149]
	v_lshl_add_u64 v[118:119], v[144:145], 0, v[142:143]
	global_store_dwordx4 v[118:119], v[132:135], off
	s_nop 1
	v_pk_mul_f32 v[134:135], v[116:117], v[146:147]
	v_pk_mul_f32 v[132:133], v[114:115], v[148:149]
	v_lshl_add_u64 v[114:115], v[144:145], 0, v[136:137]
	global_store_dwordx4 v[114:115], v[132:135], off
	s_nop 1
	v_pk_mul_f32 v[134:135], v[112:113], v[146:147]
	v_add_co_u32_e32 v112, vcc, s0, v126
	v_pk_mul_f32 v[132:133], v[110:111], v[148:149]
	s_nop 0
	v_addc_co_u32_e32 v113, vcc, 0, v127, vcc
	s_mov_b32 s0, 0x120000
	global_store_dwordx4 v[112:113], v[132:135], off
	v_lshl_add_u64 v[110:111], v[126:127], 0, s[2:3]
	s_mov_b64 s[2:3], 0x120000
	v_pk_mul_f32 v[134:135], v[108:109], v[146:147]
	v_add_co_u32_e32 v108, vcc, s0, v126
	v_pk_mul_f32 v[132:133], v[106:107], v[148:149]
	s_nop 0
	v_addc_co_u32_e32 v109, vcc, 0, v127, vcc
	s_mov_b32 s0, 0x140000
	global_store_dwordx4 v[108:109], v[132:135], off
	v_lshl_add_u64 v[106:107], v[126:127], 0, s[2:3]
	s_mov_b64 s[2:3], 0x140000
	v_pk_mul_f32 v[134:135], v[104:105], v[146:147]
	v_add_co_u32_e32 v104, vcc, s0, v126
	v_pk_mul_f32 v[132:133], v[102:103], v[148:149]
	s_nop 0
	v_addc_co_u32_e32 v105, vcc, 0, v127, vcc
	s_mov_b32 s0, 0x160000
	global_store_dwordx4 v[104:105], v[132:135], off
	v_lshl_add_u64 v[102:103], v[126:127], 0, s[2:3]
	s_mov_b64 s[2:3], 0x160000
	v_pk_mul_f32 v[134:135], v[100:101], v[146:147]
	v_add_co_u32_e32 v100, vcc, s0, v126
	v_pk_mul_f32 v[132:133], v[98:99], v[148:149]
	s_nop 0
	v_addc_co_u32_e32 v101, vcc, 0, v127, vcc
	global_store_dwordx4 v[100:101], v[132:135], off
	global_load_dwordx4 v[132:135], v[130:131], off offset:64
	v_lshl_add_u64 v[98:99], v[126:127], 0, s[2:3]
	s_waitcnt vmcnt(0)
; #define PG8_WAIT_V(n) asm volatile("s_waitcnt vmcnt(" #n ")" ::: "memory")
; #define PG8_BAR __builtin_amdgcn_s_barrier()
;     __device__ __forceinline__ void operator()(const f32x4 (&acc)[2][2][4][2], const Unit& u, int wr, int wc, int fr, int fq) const {
;     ...
;             for (int n = 0; n < 2; ++n) { const f32x4 gv = *(const f32x4*)(gp + bj * HALF + n * 16) * gs;
; #pragma unroll
;                 for (int ai = 0; ai < 2; ++ai)
; #pragma unroll
;                     for (int m = 0; m < 4; ++m) *(f32x4*)(xo + (size_t)(r0 + ai * HALF + m * 16) * DM + col0 + bj * HALF + n * 16) = gv * acc[ai][bj][m][n]; }
; template <class Epi, class Sched, bool ALIGN_EPI = false, bool SP2 = false>
; __device__ __forceinline__ void gemm_phase(LAS unsigned char* lds, const Gemm g, const Sched& S, const Epi& E) {
;     ...
;     PG8_WAIT_V(0);
;     if constexpr (!ALIGN_EPI) { if (wr == 0) PG8_BAR; }
;     PG8_BAR;
	v_pk_mul_f32 v[100:101], v[134:135], 0.5 op_sel_hi:[1,0]
	v_pk_mul_f32 v[104:105], v[132:133], 0.5 op_sel_hi:[1,0]
	v_pk_mul_f32 v[96:97], v[96:97], v[100:101]
	v_pk_mul_f32 v[94:95], v[94:95], v[104:105]
	v_pk_mul_f32 v[92:93], v[92:93], v[100:101]
	v_pk_mul_f32 v[90:91], v[90:91], v[104:105]
	v_pk_mul_f32 v[88:89], v[88:89], v[100:101]
	v_pk_mul_f32 v[86:87], v[86:87], v[104:105]
	v_pk_mul_f32 v[84:85], v[84:85], v[100:101]
	v_pk_mul_f32 v[82:83], v[82:83], v[104:105]
	v_pk_mul_f32 v[80:81], v[80:81], v[100:101]
	v_pk_mul_f32 v[78:79], v[78:79], v[104:105]
	v_pk_mul_f32 v[76:77], v[76:77], v[100:101]
	v_pk_mul_f32 v[74:75], v[74:75], v[104:105]
	v_pk_mul_f32 v[68:69], v[68:69], v[100:101]
	v_pk_mul_f32 v[66:67], v[66:67], v[104:105]
	v_pk_mul_f32 v[60:61], v[60:61], v[100:101]
	v_pk_mul_f32 v[58:59], v[58:59], v[104:105]
	global_store_dwordx4 v[126:127], v[94:97], off offset:64
	global_store_dwordx4 v[122:123], v[90:93], off offset:64
	global_store_dwordx4 v[118:119], v[86:89], off offset:64
	global_store_dwordx4 v[114:115], v[82:85], off offset:64
	global_store_dwordx4 v[110:111], v[78:81], off offset:64
	global_store_dwordx4 v[106:107], v[74:77], off offset:64
	global_store_dwordx4 v[102:103], v[66:69], off offset:64
	global_store_dwordx4 v[98:99], v[58:61], off offset:64
	global_load_dwordx4 v[58:61], v[130:131], off offset:512
	s_waitcnt vmcnt(0)
	v_pk_mul_f32 v[66:67], v[60:61], 0.5 op_sel_hi:[1,0]
	v_pk_mul_f32 v[68:69], v[58:59], 0.5 op_sel_hi:[1,0]
	v_pk_mul_f32 v[60:61], v[72:73], v[66:67]
	v_pk_mul_f32 v[58:59], v[70:71], v[68:69]
	global_store_dwordx4 v[126:127], v[58:61], off offset:512
	v_pk_mul_f32 v[56:57], v[56:57], v[66:67]
	v_pk_mul_f32 v[54:55], v[54:55], v[68:69]
	v_pk_mul_f32 v[60:61], v[64:65], v[66:67]
	v_pk_mul_f32 v[58:59], v[62:63], v[68:69]
	v_pk_mul_f32 v[52:53], v[52:53], v[66:67]
	v_pk_mul_f32 v[50:51], v[50:51], v[68:69]
	v_pk_mul_f32 v[48:49], v[48:49], v[66:67]
	v_pk_mul_f32 v[46:47], v[46:47], v[68:69]
	v_pk_mul_f32 v[40:41], v[40:41], v[66:67]
	v_pk_mul_f32 v[38:39], v[38:39], v[68:69]
	v_pk_mul_f32 v[32:33], v[32:33], v[66:67]
	v_pk_mul_f32 v[30:31], v[30:31], v[68:69]
	v_pk_mul_f32 v[24:25], v[24:25], v[66:67]
	v_pk_mul_f32 v[22:23], v[22:23], v[68:69]
	global_store_dwordx4 v[122:123], v[58:61], off offset:512
	global_store_dwordx4 v[118:119], v[54:57], off offset:512
	global_store_dwordx4 v[114:115], v[50:53], off offset:512
	global_store_dwordx4 v[110:111], v[46:49], off offset:512
	global_store_dwordx4 v[106:107], v[38:41], off offset:512
	global_store_dwordx4 v[102:103], v[30:33], off offset:512
	global_store_dwordx4 v[98:99], v[22:25], off offset:512
	global_load_dwordx4 v[22:25], v[130:131], off offset:576
	s_waitcnt vmcnt(0)
	v_pk_mul_f32 v[30:31], v[24:25], 0.5 op_sel_hi:[1,0]
	v_pk_mul_f32 v[32:33], v[22:23], 0.5 op_sel_hi:[1,0]
	v_pk_mul_f32 v[24:25], v[44:45], v[30:31]
	v_pk_mul_f32 v[22:23], v[42:43], v[32:33]
	global_store_dwordx4 v[126:127], v[22:25], off offset:576
	v_pk_mul_f32 v[20:21], v[20:21], v[30:31]
	v_pk_mul_f32 v[18:19], v[18:19], v[32:33]
	v_pk_mul_f32 v[24:25], v[36:37], v[30:31]
	v_pk_mul_f32 v[22:23], v[34:35], v[32:33]
	global_store_dwordx4 v[122:123], v[22:25], off offset:576
	v_pk_mul_f32 v[16:17], v[16:17], v[30:31]
	v_pk_mul_f32 v[14:15], v[14:15], v[32:33]
	v_pk_mul_f32 v[24:25], v[28:29], v[30:31]
	v_pk_mul_f32 v[22:23], v[26:27], v[32:33]
	v_pk_mul_f32 v[12:13], v[12:13], v[30:31]
	v_pk_mul_f32 v[10:11], v[10:11], v[32:33]
	v_pk_mul_f32 v[8:9], v[8:9], v[30:31]
	v_pk_mul_f32 v[6:7], v[6:7], v[32:33]
	v_pk_mul_f32 v[4:5], v[4:5], v[30:31]
	v_pk_mul_f32 v[2:3], v[2:3], v[32:33]
	global_store_dwordx4 v[118:119], v[22:25], off offset:576
	global_store_dwordx4 v[114:115], v[18:21], off offset:576
	global_store_dwordx4 v[110:111], v[14:17], off offset:576
	global_store_dwordx4 v[106:107], v[10:13], off offset:576
	global_store_dwordx4 v[102:103], v[6:9], off offset:576
	global_store_dwordx4 v[98:99], v[2:5], off offset:576
	s_waitcnt vmcnt(0)
	s_barrier
	s_branch .LBB0_292
.Lsync_292:
	s_mov_b32 s98, 8
.Lsync_292_loop:
	s_sleep 127
	s_sub_u32 s98, s98, 1
	s_cmp_lg_u32 s98, 0
	s_cbranch_scc1 .Lsync_292_loop

;     __device__ __forceinline__ void operator()(const f32x4 (&acc)[2][2][4][2], const Unit& u, int wr, int wc, int fr, int fq) const {
;         float* xo = part + (size_t)u.q * MC * DM + (size_t)u.pm * BM * DM;
;         const int r0 = wr * 64 + fr, col0 = u.pn * BM + wc * 32 + 4 * fq;
;         const float* gp = gate + col0;
; #pragma unroll
;         for (int bj = 0; bj < 2; ++bj)
; #pragma unroll
;             for (int n = 0; n < 2; ++n) { const f32x4 gv = *(const f32x4*)(gp + bj * HALF + n * 16) * gs;
; #pragma unroll
;                 for (int ai = 0; ai < 2; ++ai)
; #pragma unroll
;                     for (int m = 0; m < 4; ++m) *(f32x4*)(xo + (size_t)(r0 + ai * HALF + m * 16) * DM + col0 + bj * HALF + n * 16) = gv * acc[ai][bj][m][n]; }
;     }
.LBB0_1228:
	s_lshl_b32 s3, s72, 23
	s_and_b32 s3, s3, 0x1800000
	s_add_u32 s3, s73, s3
	v_readlane_b32 s1, v252, 14
	s_addc_u32 s5, s1, 0
	s_lshl_b32 s0, s0, 21
	s_add_u32 s4, s3, s0
	v_or_b32_e32 v130, 16, v134
	s_addc_u32 s5, s5, 0
	s_lshl_b32 s0, s2, 8
	v_ashrrev_i32_e32 v131, 31, v130
	v_lshl_or_b32 v1, v1, 2, s0
	v_or_b32_e32 v132, 32, v134
	v_lshlrev_b64 v[142:143], 13, v[130:131]
	v_or_b32_e32 v130, s23, v1
	v_ashrrev_i32_e32 v133, 31, v132
	v_ashrrev_i32_e32 v131, 31, v130
	v_ashrrev_i32_e32 v135, 31, v134
	v_lshlrev_b64 v[144:145], 13, v[132:133]
	v_lshlrev_b64 v[132:133], 2, v[130:131]
	v_or_b32_e32 v136, 48, v134
	v_lshlrev_b64 v[140:141], 13, v[134:135]
	v_lshl_add_u64 v[134:135], s[48:49], 0, v[132:133]
	s_mov_b32 s0, 0x92000
	v_lshl_add_u64 v[148:149], s[4:5], 0, v[132:133]
	v_add_co_u32_e32 v132, vcc, s0, v134
	s_mov_b64 s[2:3], 0x92000
	s_nop 0
	v_addc_co_u32_e32 v133, vcc, 0, v135, vcc
	v_lshl_add_u64 v[130:131], v[134:135], 0, s[2:3]
	global_load_dwordx4 v[132:135], v[132:133], off
	v_ashrrev_i32_e32 v137, 31, v136
	v_lshlrev_b64 v[146:147], 13, v[136:137]
	s_mov_b32 s0, 0x100000
	s_mov_b64 s[2:3], 0x100000
	s_waitcnt vmcnt(0)
	v_pk_mul_f32 v[138:139], v[128:129], v[134:135]
	v_pk_mul_f32 v[136:137], v[126:127], v[132:133]
	v_lshl_add_u64 v[126:127], v[148:149], 0, v[140:141]
	global_store_dwordx4 v[126:127], v[136:139], off
	s_nop 1
	v_pk_mul_f32 v[138:139], v[124:125], v[134:135]
	v_pk_mul_f32 v[136:137], v[122:123], v[132:133]
	v_lshl_add_u64 v[122:123], v[148:149], 0, v[142:143]
	global_store_dwordx4 v[122:123], v[136:139], off
	s_nop 1
	v_pk_mul_f32 v[138:139], v[120:121], v[134:135]
	v_pk_mul_f32 v[136:137], v[118:119], v[132:133]
	v_lshl_add_u64 v[118:119], v[148:149], 0, v[144:145]
	global_store_dwordx4 v[118:119], v[136:139], off
	s_nop 1
	v_pk_mul_f32 v[138:139], v[116:117], v[134:135]
	v_pk_mul_f32 v[136:137], v[114:115], v[132:133]
	v_lshl_add_u64 v[114:115], v[148:149], 0, v[146:147]
	global_store_dwordx4 v[114:115], v[136:139], off
	s_nop 1
	v_pk_mul_f32 v[138:139], v[112:113], v[134:135]
	v_add_co_u32_e32 v112, vcc, s0, v126
	v_pk_mul_f32 v[136:137], v[110:111], v[132:133]
	s_nop 0
	v_addc_co_u32_e32 v113, vcc, 0, v127, vcc
	s_mov_b32 s0, 0x120000
	global_store_dwordx4 v[112:113], v[136:139], off
	v_lshl_add_u64 v[110:111], v[126:127], 0, s[2:3]
	s_mov_b64 s[2:3], 0x120000
	v_pk_mul_f32 v[138:139], v[108:109], v[134:135]
	v_add_co_u32_e32 v108, vcc, s0, v126
	v_pk_mul_f32 v[136:137], v[106:107], v[132:133]
	s_nop 0
	v_addc_co_u32_e32 v109, vcc, 0, v127, vcc
	s_mov_b32 s0, 0x140000
	global_store_dwordx4 v[108:109], v[136:139], off
	v_lshl_add_u64 v[106:107], v[126:127], 0, s[2:3]
	s_mov_b64 s[2:3], 0x140000
	v_pk_mul_f32 v[138:139], v[104:105], v[134:135]
	v_add_co_u32_e32 v104, vcc, s0, v126
	s_mov_b32 s0, 0x160000
	s_nop 0
	v_addc_co_u32_e32 v105, vcc, 0, v127, vcc
	v_pk_mul_f32 v[134:135], v[100:101], v[134:135]
	v_add_co_u32_e32 v100, vcc, s0, v126
	v_pk_mul_f32 v[136:137], v[102:103], v[132:133]
	v_pk_mul_f32 v[132:133], v[98:99], v[132:133]
	v_addc_co_u32_e32 v101, vcc, 0, v127, vcc
	global_store_dwordx4 v[104:105], v[136:139], off
	global_store_dwordx4 v[100:101], v[132:135], off
	global_load_dwordx4 v[132:135], v[130:131], off offset:64
	v_lshl_add_u64 v[102:103], v[126:127], 0, s[2:3]
	s_mov_b64 s[2:3], 0x160000
	v_lshl_add_u64 v[98:99], v[126:127], 0, s[2:3]
	s_waitcnt vmcnt(0)
	v_pk_mul_f32 v[96:97], v[96:97], v[134:135]
	v_pk_mul_f32 v[94:95], v[94:95], v[132:133]
	v_pk_mul_f32 v[92:93], v[92:93], v[134:135]
	v_pk_mul_f32 v[90:91], v[90:91], v[132:133]
	v_pk_mul_f32 v[88:89], v[88:89], v[134:135]
	v_pk_mul_f32 v[86:87], v[86:87], v[132:133]
	v_pk_mul_f32 v[84:85], v[84:85], v[134:135]
	v_pk_mul_f32 v[82:83], v[82:83], v[132:133]
	v_pk_mul_f32 v[80:81], v[80:81], v[134:135]
	v_pk_mul_f32 v[78:79], v[78:79], v[132:133]
	v_pk_mul_f32 v[76:77], v[76:77], v[134:135]
	v_pk_mul_f32 v[74:75], v[74:75], v[132:133]
	v_pk_mul_f32 v[68:69], v[68:69], v[134:135]
	v_pk_mul_f32 v[66:67], v[66:67], v[132:133]
	v_pk_mul_f32 v[60:61], v[60:61], v[134:135]
	v_pk_mul_f32 v[58:59], v[58:59], v[132:133]
	global_store_dwordx4 v[126:127], v[94:97], off offset:64
	global_store_dwordx4 v[122:123], v[90:93], off offset:64
	global_store_dwordx4 v[118:119], v[86:89], off offset:64
	global_store_dwordx4 v[114:115], v[82:85], off offset:64
	global_store_dwordx4 v[110:111], v[78:81], off offset:64
	global_store_dwordx4 v[106:107], v[74:77], off offset:64
	global_store_dwordx4 v[102:103], v[66:69], off offset:64
	global_store_dwordx4 v[98:99], v[58:61], off offset:64
	global_load_dwordx4 v[58:61], v[130:131], off offset:512
	s_waitcnt vmcnt(0)
	v_pk_mul_f32 v[68:69], v[72:73], v[60:61]
	v_pk_mul_f32 v[66:67], v[70:71], v[58:59]
	v_pk_mul_f32 v[64:65], v[64:65], v[60:61]
	v_pk_mul_f32 v[62:63], v[62:63], v[58:59]
	v_pk_mul_f32 v[56:57], v[56:57], v[60:61]
	v_pk_mul_f32 v[54:55], v[54:55], v[58:59]
	v_pk_mul_f32 v[52:53], v[52:53], v[60:61]
	v_pk_mul_f32 v[50:51], v[50:51], v[58:59]
	v_pk_mul_f32 v[48:49], v[48:49], v[60:61]
	v_pk_mul_f32 v[46:47], v[46:47], v[58:59]
	v_pk_mul_f32 v[40:41], v[40:41], v[60:61]
	v_pk_mul_f32 v[38:39], v[38:39], v[58:59]
	v_pk_mul_f32 v[32:33], v[32:33], v[60:61]
	v_pk_mul_f32 v[30:31], v[30:31], v[58:59]
	v_pk_mul_f32 v[24:25], v[24:25], v[60:61]
	v_pk_mul_f32 v[22:23], v[22:23], v[58:59]
	global_store_dwordx4 v[126:127], v[66:69], off offset:512
	global_store_dwordx4 v[122:123], v[62:65], off offset:512
	global_store_dwordx4 v[118:119], v[54:57], off offset:512
	global_store_dwordx4 v[114:115], v[50:53], off offset:512
	global_store_dwordx4 v[110:111], v[46:49], off offset:512
	global_store_dwordx4 v[106:107], v[38:41], off offset:512
	global_store_dwordx4 v[102:103], v[30:33], off offset:512
	global_store_dwordx4 v[98:99], v[22:25], off offset:512
	global_load_dwordx4 v[22:25], v[130:131], off offset:576
	s_waitcnt vmcnt(0)
	v_pk_mul_f32 v[32:33], v[44:45], v[24:25]
	v_pk_mul_f32 v[30:31], v[42:43], v[22:23]
	global_store_dwordx4 v[126:127], v[30:33], off offset:576
	v_pk_mul_f32 v[28:29], v[28:29], v[24:25]
	v_pk_mul_f32 v[26:27], v[26:27], v[22:23]
	v_pk_mul_f32 v[32:33], v[36:37], v[24:25]
	v_pk_mul_f32 v[30:31], v[34:35], v[22:23]
	v_pk_mul_f32 v[20:21], v[20:21], v[24:25]
	v_pk_mul_f32 v[18:19], v[18:19], v[22:23]
	v_pk_mul_f32 v[16:17], v[16:17], v[24:25]
	v_pk_mul_f32 v[14:15], v[14:15], v[22:23]
	v_pk_mul_f32 v[12:13], v[12:13], v[24:25]
	v_pk_mul_f32 v[10:11], v[10:11], v[22:23]
	v_pk_mul_f32 v[8:9], v[8:9], v[24:25]
	v_pk_mul_f32 v[6:7], v[6:7], v[22:23]
	v_pk_mul_f32 v[4:5], v[4:5], v[24:25]
	v_pk_mul_f32 v[2:3], v[2:3], v[22:23]
	global_store_dwordx4 v[122:123], v[30:33], off offset:576
	global_store_dwordx4 v[118:119], v[26:29], off offset:576
	global_store_dwordx4 v[114:115], v[18:21], off offset:576
	global_store_dwordx4 v[110:111], v[14:17], off offset:576
	global_store_dwordx4 v[106:107], v[10:13], off offset:576
	global_store_dwordx4 v[102:103], v[6:9], off offset:576
	global_store_dwordx4 v[98:99], v[2:5], off offset:576
	s_waitcnt vmcnt(0)
	s_barrier
; #define PG8_WAIT_V(n) asm volatile("s_waitcnt vmcnt(" #n ")" ::: "memory")
; #define PG8_BAR __builtin_amdgcn_s_barrier()
; template <class Epi, class Sched, bool ALIGN_EPI = false, bool SP2 = false>
; __device__ __forceinline__ void gemm_phase(LAS unsigned char* lds, const Gemm g, const Sched& S, const Epi& E) {
;     ...
;     PG8_WAIT_V(0);
;     if constexpr (!ALIGN_EPI) { if (wr == 0) PG8_BAR; }
;     PG8_BAR;
	s_branch .LBB0_1229

;     __device__ __forceinline__ void operator()(const f32x4 (&acc)[2][2][4][2], const Unit& u, int wr, int wc, int fr, int fq) const {
;         float* xo = part + (size_t)u.q * MC * DM + (size_t)u.pm * BM * DM;
;         const int r0 = wr * 64 + fr, col0 = u.pn * BM + wc * 32 + 4 * fq;
;         const float* gp = gate + col0;
; #pragma unroll
;         for (int bj = 0; bj < 2; ++bj)
; #pragma unroll
;             for (int n = 0; n < 2; ++n) { const f32x4 gv = *(const f32x4*)(gp + bj * HALF + n * 16) * gs;
; #pragma unroll
;                 for (int ai = 0; ai < 2; ++ai)
; #pragma unroll
;                     for (int m = 0; m < 4; ++m) *(f32x4*)(xo + (size_t)(r0 + ai * HALF + m * 16) * DM + col0 + bj * HALF + n * 16) = gv * acc[ai][bj][m][n]; }
;     }
.LBB0_1568:
	s_lshl_b32 s2, s1, 23
	s_and_b32 s2, s2, 0x1800000
	s_add_u32 s2, s73, s2
	s_addc_u32 s3, s72, 0
	s_lshl_b32 s8, s20, 21
	s_add_u32 s2, s2, s8
	v_or_b32_e32 v130, 16, v134
	s_addc_u32 s3, s3, 0
	s_lshl_b32 s0, s0, 8
	v_ashrrev_i32_e32 v131, 31, v130
	v_lshl_or_b32 v1, v1, 2, s0
	v_or_b32_e32 v132, 32, v134
	v_lshlrev_b64 v[140:141], 13, v[130:131]
	v_or_b32_e32 v130, s23, v1
	v_ashrrev_i32_e32 v133, 31, v132
	v_ashrrev_i32_e32 v131, 31, v130
	v_readlane_b32 s48, v253, 38
	v_ashrrev_i32_e32 v135, 31, v134
	v_lshlrev_b64 v[142:143], 13, v[132:133]
	v_lshlrev_b64 v[132:133], 2, v[130:131]
	v_readlane_b32 s49, v253, 39
	v_or_b32_e32 v136, 48, v134
	v_lshlrev_b64 v[138:139], 13, v[134:135]
	v_lshl_add_u64 v[134:135], s[48:49], 0, v[132:133]
	s_mov_b32 s0, 0x98000
	v_lshl_add_u64 v[144:145], s[2:3], 0, v[132:133]
	v_add_co_u32_e32 v132, vcc, s0, v134
	s_mov_b64 s[8:9], 0x98000
	s_nop 0
	v_addc_co_u32_e32 v133, vcc, 0, v135, vcc
	v_lshl_add_u64 v[130:131], v[134:135], 0, s[8:9]
	global_load_dwordx4 v[132:135], v[132:133], off
	v_ashrrev_i32_e32 v137, 31, v136
	v_lshlrev_b64 v[136:137], 13, v[136:137]
	s_mov_b32 s0, 0x100000
	s_mov_b64 s[2:3], 0x100000
	v_readlane_b32 s30, v252, 2
	v_readlane_b32 s34, v252, 37
	v_readlane_b32 s50, v253, 40
	v_readlane_b32 s51, v253, 41
	v_readlane_b32 s31, v252, 3
	v_readlane_b32 s35, v252, 38
	s_waitcnt vmcnt(0)
	v_pk_mul_f32 v[146:147], v[134:135], 0.5 op_sel_hi:[1,0]
	v_pk_mul_f32 v[148:149], v[132:133], 0.5 op_sel_hi:[1,0]
	v_pk_mul_f32 v[134:135], v[128:129], v[146:147]
	v_pk_mul_f32 v[132:133], v[126:127], v[148:149]
	v_lshl_add_u64 v[126:127], v[144:145], 0, v[138:139]
	global_store_dwordx4 v[126:127], v[132:135], off
	s_nop 1
	v_pk_mul_f32 v[134:135], v[124:125], v[146:147]
	v_pk_mul_f32 v[132:133], v[122:123], v[148:149]
	v_lshl_add_u64 v[122:123], v[144:145], 0, v[140:141]
	global_store_dwordx4 v[122:123], v[132:135], off
	s_nop 1
	v_pk_mul_f32 v[134:135], v[120:121], v[146:147]
	v_pk_mul_f32 v[132:133], v[118:119], v[148:149]
	v_lshl_add_u64 v[118:119], v[144:145], 0, v[142:143]
	global_store_dwordx4 v[118:119], v[132:135], off
	s_nop 1
	v_pk_mul_f32 v[134:135], v[116:117], v[146:147]
	v_pk_mul_f32 v[132:133], v[114:115], v[148:149]
	v_lshl_add_u64 v[114:115], v[144:145], 0, v[136:137]
	global_store_dwordx4 v[114:115], v[132:135], off
	s_nop 1
	v_pk_mul_f32 v[134:135], v[112:113], v[146:147]
	v_add_co_u32_e32 v112, vcc, s0, v126
	v_pk_mul_f32 v[132:133], v[110:111], v[148:149]
	s_nop 0
	v_addc_co_u32_e32 v113, vcc, 0, v127, vcc
	s_mov_b32 s0, 0x120000
	global_store_dwordx4 v[112:113], v[132:135], off
	v_lshl_add_u64 v[110:111], v[126:127], 0, s[2:3]
	s_mov_b64 s[2:3], 0x120000
	v_pk_mul_f32 v[134:135], v[108:109], v[146:147]
	v_add_co_u32_e32 v108, vcc, s0, v126
	v_pk_mul_f32 v[132:133], v[106:107], v[148:149]
	s_nop 0
	v_addc_co_u32_e32 v109, vcc, 0, v127, vcc
	s_mov_b32 s0, 0x140000
	global_store_dwordx4 v[108:109], v[132:135], off
	v_lshl_add_u64 v[106:107], v[126:127], 0, s[2:3]
	s_mov_b64 s[2:3], 0x140000
	v_pk_mul_f32 v[134:135], v[104:105], v[146:147]
	v_add_co_u32_e32 v104, vcc, s0, v126
	v_pk_mul_f32 v[132:133], v[102:103], v[148:149]
	s_nop 0
	v_addc_co_u32_e32 v105, vcc, 0, v127, vcc
	s_mov_b32 s0, 0x160000
	global_store_dwordx4 v[104:105], v[132:135], off
	v_lshl_add_u64 v[102:103], v[126:127], 0, s[2:3]
	s_mov_b64 s[2:3], 0x160000
	v_pk_mul_f32 v[134:135], v[100:101], v[146:147]
	v_add_co_u32_e32 v100, vcc, s0, v126
	v_pk_mul_f32 v[132:133], v[98:99], v[148:149]
	s_nop 0
	v_addc_co_u32_e32 v101, vcc, 0, v127, vcc
	global_store_dwordx4 v[100:101], v[132:135], off
	global_load_dwordx4 v[132:135], v[130:131], off offset:64
	v_lshl_add_u64 v[98:99], v[126:127], 0, s[2:3]
	s_waitcnt vmcnt(0)
; #define PG8_WAIT_V(n) asm volatile("s_waitcnt vmcnt(" #n ")" ::: "memory")
; #define PG8_BAR __builtin_amdgcn_s_barrier()
;     __device__ __forceinline__ void operator()(const f32x4 (&acc)[2][2][4][2], const Unit& u, int wr, int wc, int fr, int fq) const {
;     ...
;             for (int n = 0; n < 2; ++n) { const f32x4 gv = *(const f32x4*)(gp + bj * HALF + n * 16) * gs;
; #pragma unroll
;                 for (int ai = 0; ai < 2; ++ai)
; #pragma unroll
;                     for (int m = 0; m < 4; ++m) *(f32x4*)(xo + (size_t)(r0 + ai * HALF + m * 16) * DM + col0 + bj * HALF + n * 16) = gv * acc[ai][bj][m][n]; }
; template <class Epi, class Sched, bool ALIGN_EPI = false, bool SP2 = false>
; __device__ __forceinline__ void gemm_phase(LAS unsigned char* lds, const Gemm g, const Sched& S, const Epi& E) {
;     ...
;     PG8_WAIT_V(0);
;     if constexpr (!ALIGN_EPI) { if (wr == 0) PG8_BAR; }
;     PG8_BAR;
	v_pk_mul_f32 v[100:101], v[134:135], 0.5 op_sel_hi:[1,0]
	v_pk_mul_f32 v[104:105], v[132:133], 0.5 op_sel_hi:[1,0]
	v_pk_mul_f32 v[96:97], v[96:97], v[100:101]
	v_pk_mul_f32 v[94:95], v[94:95], v[104:105]
	v_pk_mul_f32 v[92:93], v[92:93], v[100:101]
	v_pk_mul_f32 v[90:91], v[90:91], v[104:105]
	v_pk_mul_f32 v[88:89], v[88:89], v[100:101]
	v_pk_mul_f32 v[86:87], v[86:87], v[104:105]
	v_pk_mul_f32 v[84:85], v[84:85], v[100:101]
	v_pk_mul_f32 v[82:83], v[82:83], v[104:105]
	v_pk_mul_f32 v[80:81], v[80:81], v[100:101]
	v_pk_mul_f32 v[78:79], v[78:79], v[104:105]
	v_pk_mul_f32 v[76:77], v[76:77], v[100:101]
	v_pk_mul_f32 v[74:75], v[74:75], v[104:105]
	v_pk_mul_f32 v[68:69], v[68:69], v[100:101]
	v_pk_mul_f32 v[66:67], v[66:67], v[104:105]
	v_pk_mul_f32 v[60:61], v[60:61], v[100:101]
	v_pk_mul_f32 v[58:59], v[58:59], v[104:105]
	global_store_dwordx4 v[126:127], v[94:97], off offset:64
	global_store_dwordx4 v[122:123], v[90:93], off offset:64
	global_store_dwordx4 v[118:119], v[86:89], off offset:64
	global_store_dwordx4 v[114:115], v[82:85], off offset:64
	global_store_dwordx4 v[110:111], v[78:81], off offset:64
	global_store_dwordx4 v[106:107], v[74:77], off offset:64
	global_store_dwordx4 v[102:103], v[66:69], off offset:64
	global_store_dwordx4 v[98:99], v[58:61], off offset:64
	global_load_dwordx4 v[58:61], v[130:131], off offset:512
	s_waitcnt vmcnt(0)
	v_pk_mul_f32 v[66:67], v[60:61], 0.5 op_sel_hi:[1,0]
	v_pk_mul_f32 v[68:69], v[58:59], 0.5 op_sel_hi:[1,0]
	v_pk_mul_f32 v[60:61], v[72:73], v[66:67]
	v_pk_mul_f32 v[58:59], v[70:71], v[68:69]
	global_store_dwordx4 v[126:127], v[58:61], off offset:512
	v_pk_mul_f32 v[56:57], v[56:57], v[66:67]
	v_pk_mul_f32 v[54:55], v[54:55], v[68:69]
	v_pk_mul_f32 v[60:61], v[64:65], v[66:67]
	v_pk_mul_f32 v[58:59], v[62:63], v[68:69]
	v_pk_mul_f32 v[52:53], v[52:53], v[66:67]
	v_pk_mul_f32 v[50:51], v[50:51], v[68:69]
	v_pk_mul_f32 v[48:49], v[48:49], v[66:67]
	v_pk_mul_f32 v[46:47], v[46:47], v[68:69]
	v_pk_mul_f32 v[40:41], v[40:41], v[66:67]
	v_pk_mul_f32 v[38:39], v[38:39], v[68:69]
	v_pk_mul_f32 v[32:33], v[32:33], v[66:67]
	v_pk_mul_f32 v[30:31], v[30:31], v[68:69]
	v_pk_mul_f32 v[24:25], v[24:25], v[66:67]
	v_pk_mul_f32 v[22:23], v[22:23], v[68:69]
	global_store_dwordx4 v[122:123], v[58:61], off offset:512
	global_store_dwordx4 v[118:119], v[54:57], off offset:512
	global_store_dwordx4 v[114:115], v[50:53], off offset:512
	global_store_dwordx4 v[110:111], v[46:49], off offset:512
	global_store_dwordx4 v[106:107], v[38:41], off offset:512
	global_store_dwordx4 v[102:103], v[30:33], off offset:512
	global_store_dwordx4 v[98:99], v[22:25], off offset:512
	global_load_dwordx4 v[22:25], v[130:131], off offset:576
	s_waitcnt vmcnt(0)
	v_pk_mul_f32 v[30:31], v[24:25], 0.5 op_sel_hi:[1,0]
	v_pk_mul_f32 v[32:33], v[22:23], 0.5 op_sel_hi:[1,0]
	v_pk_mul_f32 v[24:25], v[44:45], v[30:31]
	v_pk_mul_f32 v[22:23], v[42:43], v[32:33]
	global_store_dwordx4 v[126:127], v[22:25], off offset:576
	v_pk_mul_f32 v[20:21], v[20:21], v[30:31]
	v_pk_mul_f32 v[18:19], v[18:19], v[32:33]
	v_pk_mul_f32 v[24:25], v[36:37], v[30:31]
	v_pk_mul_f32 v[22:23], v[34:35], v[32:33]
	global_store_dwordx4 v[122:123], v[22:25], off offset:576
	v_pk_mul_f32 v[16:17], v[16:17], v[30:31]
	v_pk_mul_f32 v[14:15], v[14:15], v[32:33]
	v_pk_mul_f32 v[24:25], v[28:29], v[30:31]
	v_pk_mul_f32 v[22:23], v[26:27], v[32:33]
	v_pk_mul_f32 v[12:13], v[12:13], v[30:31]
	v_pk_mul_f32 v[10:11], v[10:11], v[32:33]
	v_pk_mul_f32 v[8:9], v[8:9], v[30:31]
	v_pk_mul_f32 v[6:7], v[6:7], v[32:33]
	v_pk_mul_f32 v[4:5], v[4:5], v[30:31]
	v_pk_mul_f32 v[2:3], v[2:3], v[32:33]
	global_store_dwordx4 v[118:119], v[22:25], off offset:576
	global_store_dwordx4 v[114:115], v[18:21], off offset:576
	global_store_dwordx4 v[110:111], v[14:17], off offset:576
	global_store_dwordx4 v[106:107], v[10:13], off offset:576
	global_store_dwordx4 v[102:103], v[6:9], off offset:576
	global_store_dwordx4 v[98:99], v[2:5], off offset:576
	s_waitcnt vmcnt(0)
	s_barrier
	s_branch .LBB0_1569

;     __device__ __forceinline__ void operator()(const f32x4 (&acc)[2][2][4][2], const Unit& u, int wr, int wc, int fr, int fq) const {
;         float* xo = part + (size_t)u.q * MC * DM + (size_t)u.pm * BM * DM;
;         const int r0 = wr * 64 + fr, col0 = u.pn * BM + wc * 32 + 4 * fq;
;         const float* gp = gate + col0;
; #pragma unroll
;         for (int bj = 0; bj < 2; ++bj)
; #pragma unroll
;             for (int n = 0; n < 2; ++n) { const f32x4 gv = *(const f32x4*)(gp + bj * HALF + n * 16) * gs;
; #pragma unroll
;                 for (int ai = 0; ai < 2; ++ai)
; #pragma unroll
;                     for (int m = 0; m < 4; ++m) *(f32x4*)(xo + (size_t)(r0 + ai * HALF + m * 16) * DM + col0 + bj * HALF + n * 16) = gv * acc[ai][bj][m][n]; }
;     }
.LBB0_1899:
	s_lshl_b32 s2, s1, 23
	s_and_b32 s2, s2, 0x1800000
	s_add_u32 s2, s73, s2
	s_addc_u32 s3, s72, 0
	s_lshl_b32 s4, s18, 21
	s_add_u32 s2, s2, s4
	v_or_b32_e32 v130, 16, v134
	s_addc_u32 s3, s3, 0
	s_lshl_b32 s0, s0, 8
	v_ashrrev_i32_e32 v131, 31, v130
	v_lshl_or_b32 v1, v1, 2, s0
	v_or_b32_e32 v132, 32, v134
	v_lshlrev_b64 v[140:141], 13, v[130:131]
	v_or_b32_e32 v130, s21, v1
	v_ashrrev_i32_e32 v133, 31, v132
	v_ashrrev_i32_e32 v131, 31, v130
	v_ashrrev_i32_e32 v135, 31, v134
	v_lshlrev_b64 v[142:143], 13, v[132:133]
	v_lshlrev_b64 v[132:133], 2, v[130:131]
	v_or_b32_e32 v136, 48, v134
	v_lshlrev_b64 v[138:139], 13, v[134:135]
	v_lshl_add_u64 v[134:135], s[48:49], 0, v[132:133]
	s_mov_b32 s0, 0xe6000
	v_lshl_add_u64 v[144:145], s[2:3], 0, v[132:133]
	v_add_co_u32_e32 v132, vcc, s0, v134
	s_mov_b64 s[4:5], 0xe6000
	s_nop 0
	v_addc_co_u32_e32 v133, vcc, 0, v135, vcc
	v_lshl_add_u64 v[130:131], v[134:135], 0, s[4:5]
	global_load_dwordx4 v[132:135], v[132:133], off
	v_ashrrev_i32_e32 v137, 31, v136
	v_lshlrev_b64 v[136:137], 13, v[136:137]
	s_mov_b32 s0, 0x100000
	s_mov_b64 s[2:3], 0x100000
	s_waitcnt vmcnt(0)
	v_pk_mul_f32 v[146:147], v[134:135], 0.5 op_sel_hi:[1,0]
	v_pk_mul_f32 v[148:149], v[132:133], 0.5 op_sel_hi:[1,0]
	v_pk_mul_f32 v[134:135], v[128:129], v[146:147]
	v_pk_mul_f32 v[132:133], v[126:127], v[148:149]
	v_lshl_add_u64 v[126:127], v[144:145], 0, v[138:139]
	global_store_dwordx4 v[126:127], v[132:135], off
	s_nop 1
	v_pk_mul_f32 v[134:135], v[124:125], v[146:147]
	v_pk_mul_f32 v[132:133], v[122:123], v[148:149]
	v_lshl_add_u64 v[122:123], v[144:145], 0, v[140:141]
	global_store_dwordx4 v[122:123], v[132:135], off
	s_nop 1
	v_pk_mul_f32 v[134:135], v[120:121], v[146:147]
	v_pk_mul_f32 v[132:133], v[118:119], v[148:149]
	v_lshl_add_u64 v[118:119], v[144:145], 0, v[142:143]
	global_store_dwordx4 v[118:119], v[132:135], off
	s_nop 1
	v_pk_mul_f32 v[134:135], v[116:117], v[146:147]
	v_pk_mul_f32 v[132:133], v[114:115], v[148:149]
	v_lshl_add_u64 v[114:115], v[144:145], 0, v[136:137]
	global_store_dwordx4 v[114:115], v[132:135], off
	s_nop 1
	v_pk_mul_f32 v[134:135], v[112:113], v[146:147]
	v_add_co_u32_e32 v112, vcc, s0, v126
	v_pk_mul_f32 v[132:133], v[110:111], v[148:149]
	s_nop 0
	v_addc_co_u32_e32 v113, vcc, 0, v127, vcc
	s_mov_b32 s0, 0x120000
	global_store_dwordx4 v[112:113], v[132:135], off
	v_lshl_add_u64 v[110:111], v[126:127], 0, s[2:3]
	s_mov_b64 s[2:3], 0x120000
	v_pk_mul_f32 v[134:135], v[108:109], v[146:147]
	v_add_co_u32_e32 v108, vcc, s0, v126
	v_pk_mul_f32 v[132:133], v[106:107], v[148:149]
	s_nop 0
	v_addc_co_u32_e32 v109, vcc, 0, v127, vcc
	s_mov_b32 s0, 0x140000
	global_store_dwordx4 v[108:109], v[132:135], off
	v_lshl_add_u64 v[106:107], v[126:127], 0, s[2:3]
	s_mov_b64 s[2:3], 0x140000
	v_pk_mul_f32 v[134:135], v[104:105], v[146:147]
	v_add_co_u32_e32 v104, vcc, s0, v126
	v_pk_mul_f32 v[132:133], v[102:103], v[148:149]
	s_nop 0
	v_addc_co_u32_e32 v105, vcc, 0, v127, vcc
	s_mov_b32 s0, 0x160000
	global_store_dwordx4 v[104:105], v[132:135], off
	v_lshl_add_u64 v[102:103], v[126:127], 0, s[2:3]
	s_mov_b64 s[2:3], 0x160000
	v_pk_mul_f32 v[134:135], v[100:101], v[146:147]
	v_add_co_u32_e32 v100, vcc, s0, v126
	v_pk_mul_f32 v[132:133], v[98:99], v[148:149]
	s_nop 0
	v_addc_co_u32_e32 v101, vcc, 0, v127, vcc
	global_store_dwordx4 v[100:101], v[132:135], off
	global_load_dwordx4 v[132:135], v[130:131], off offset:64
	v_lshl_add_u64 v[98:99], v[126:127], 0, s[2:3]
	s_waitcnt vmcnt(0)
; #define PG8_WAIT_V(n) asm volatile("s_waitcnt vmcnt(" #n ")" ::: "memory")
; #define PG8_BAR __builtin_amdgcn_s_barrier()
;     __device__ __forceinline__ void operator()(const f32x4 (&acc)[2][2][4][2], const Unit& u, int wr, int wc, int fr, int fq) const {
;     ...
;             for (int n = 0; n < 2; ++n) { const f32x4 gv = *(const f32x4*)(gp + bj * HALF + n * 16) * gs;
; #pragma unroll
;                 for (int ai = 0; ai < 2; ++ai)
; #pragma unroll
;                     for (int m = 0; m < 4; ++m) *(f32x4*)(xo + (size_t)(r0 + ai * HALF + m * 16) * DM + col0 + bj * HALF + n * 16) = gv * acc[ai][bj][m][n]; }
; template <class Epi, class Sched, bool ALIGN_EPI = false, bool SP2 = false>
; __device__ __forceinline__ void gemm_phase(LAS unsigned char* lds, const Gemm g, const Sched& S, const Epi& E) {
;     ...
;     PG8_WAIT_V(0);
;     if constexpr (!ALIGN_EPI) { if (wr == 0) PG8_BAR; }
;     PG8_BAR;
	v_pk_mul_f32 v[100:101], v[134:135], 0.5 op_sel_hi:[1,0]
	v_pk_mul_f32 v[104:105], v[132:133], 0.5 op_sel_hi:[1,0]
	v_pk_mul_f32 v[96:97], v[96:97], v[100:101]
	v_pk_mul_f32 v[94:95], v[94:95], v[104:105]
	v_pk_mul_f32 v[92:93], v[92:93], v[100:101]
	v_pk_mul_f32 v[90:91], v[90:91], v[104:105]
	v_pk_mul_f32 v[88:89], v[88:89], v[100:101]
	v_pk_mul_f32 v[86:87], v[86:87], v[104:105]
	v_pk_mul_f32 v[84:85], v[84:85], v[100:101]
	v_pk_mul_f32 v[82:83], v[82:83], v[104:105]
	v_pk_mul_f32 v[80:81], v[80:81], v[100:101]
	v_pk_mul_f32 v[78:79], v[78:79], v[104:105]
	v_pk_mul_f32 v[76:77], v[76:77], v[100:101]
	v_pk_mul_f32 v[74:75], v[74:75], v[104:105]
	v_pk_mul_f32 v[68:69], v[68:69], v[100:101]
	v_pk_mul_f32 v[66:67], v[66:67], v[104:105]
	v_pk_mul_f32 v[60:61], v[60:61], v[100:101]
	v_pk_mul_f32 v[58:59], v[58:59], v[104:105]
	global_store_dwordx4 v[126:127], v[94:97], off offset:64
	global_store_dwordx4 v[122:123], v[90:93], off offset:64
	global_store_dwordx4 v[118:119], v[86:89], off offset:64
	global_store_dwordx4 v[114:115], v[82:85], off offset:64
	global_store_dwordx4 v[110:111], v[78:81], off offset:64
	global_store_dwordx4 v[106:107], v[74:77], off offset:64
	global_store_dwordx4 v[102:103], v[66:69], off offset:64
	global_store_dwordx4 v[98:99], v[58:61], off offset:64
	global_load_dwordx4 v[58:61], v[130:131], off offset:512
	s_waitcnt vmcnt(0)
	v_pk_mul_f32 v[66:67], v[60:61], 0.5 op_sel_hi:[1,0]
	v_pk_mul_f32 v[68:69], v[58:59], 0.5 op_sel_hi:[1,0]
	v_pk_mul_f32 v[60:61], v[72:73], v[66:67]
	v_pk_mul_f32 v[58:59], v[70:71], v[68:69]
	global_store_dwordx4 v[126:127], v[58:61], off offset:512
	v_pk_mul_f32 v[56:57], v[56:57], v[66:67]
	v_pk_mul_f32 v[54:55], v[54:55], v[68:69]
	v_pk_mul_f32 v[60:61], v[64:65], v[66:67]
	v_pk_mul_f32 v[58:59], v[62:63], v[68:69]
	v_pk_mul_f32 v[52:53], v[52:53], v[66:67]
	v_pk_mul_f32 v[50:51], v[50:51], v[68:69]
	v_pk_mul_f32 v[48:49], v[48:49], v[66:67]
	v_pk_mul_f32 v[46:47], v[46:47], v[68:69]
	v_pk_mul_f32 v[40:41], v[40:41], v[66:67]
	v_pk_mul_f32 v[38:39], v[38:39], v[68:69]
	v_pk_mul_f32 v[32:33], v[32:33], v[66:67]
	v_pk_mul_f32 v[30:31], v[30:31], v[68:69]
	v_pk_mul_f32 v[24:25], v[24:25], v[66:67]
	v_pk_mul_f32 v[22:23], v[22:23], v[68:69]
	global_store_dwordx4 v[122:123], v[58:61], off offset:512
	global_store_dwordx4 v[118:119], v[54:57], off offset:512
	global_store_dwordx4 v[114:115], v[50:53], off offset:512
	global_store_dwordx4 v[110:111], v[46:49], off offset:512
	global_store_dwordx4 v[106:107], v[38:41], off offset:512
	global_store_dwordx4 v[102:103], v[30:33], off offset:512
	global_store_dwordx4 v[98:99], v[22:25], off offset:512
	global_load_dwordx4 v[22:25], v[130:131], off offset:576
	s_waitcnt vmcnt(0)
	v_pk_mul_f32 v[30:31], v[24:25], 0.5 op_sel_hi:[1,0]
	v_pk_mul_f32 v[32:33], v[22:23], 0.5 op_sel_hi:[1,0]
	v_pk_mul_f32 v[24:25], v[44:45], v[30:31]
	v_pk_mul_f32 v[22:23], v[42:43], v[32:33]
	global_store_dwordx4 v[126:127], v[22:25], off offset:576
	v_pk_mul_f32 v[20:21], v[20:21], v[30:31]
	v_pk_mul_f32 v[18:19], v[18:19], v[32:33]
	v_pk_mul_f32 v[24:25], v[36:37], v[30:31]
	v_pk_mul_f32 v[22:23], v[34:35], v[32:33]
	global_store_dwordx4 v[122:123], v[22:25], off offset:576
	v_pk_mul_f32 v[16:17], v[16:17], v[30:31]
	v_pk_mul_f32 v[14:15], v[14:15], v[32:33]
	v_pk_mul_f32 v[24:25], v[28:29], v[30:31]
	v_pk_mul_f32 v[22:23], v[26:27], v[32:33]
	v_pk_mul_f32 v[12:13], v[12:13], v[30:31]
	v_pk_mul_f32 v[10:11], v[10:11], v[32:33]
	v_pk_mul_f32 v[8:9], v[8:9], v[30:31]
	v_pk_mul_f32 v[6:7], v[6:7], v[32:33]
	v_pk_mul_f32 v[4:5], v[4:5], v[30:31]
	v_pk_mul_f32 v[2:3], v[2:3], v[32:33]
	global_store_dwordx4 v[118:119], v[22:25], off offset:576
	global_store_dwordx4 v[114:115], v[18:21], off offset:576
	global_store_dwordx4 v[110:111], v[14:17], off offset:576
	global_store_dwordx4 v[106:107], v[10:13], off offset:576
	global_store_dwordx4 v[102:103], v[6:9], off offset:576
	global_store_dwordx4 v[98:99], v[2:5], off offset:576
	s_waitcnt vmcnt(0)
	s_barrier
	s_branch .LBB0_1900
